# P3 delta items: 16-lane sum-of-squares reductions done with DPP adds instead of ds_bpermute round trips
# speedup vs baseline: 1.0061x; 1.0061x over previous
.LBB0_313:
	v_add_u32_e32 v230, 0, v146
	v_add_u32_e32 v34, s49, v146
	ds_write_b128 v230, v[234:237] offset:54272
	ds_write_b128 v209, v[234:237] offset:54272
	ds_write_b128 v210, v[234:237] offset:54272
	s_and_saveexec_b64 s[2:3], s[42:43]
	ds_write_b128 v34, v[30:33] offset:6144
	s_or_b64 exec, exec, s[2:3]
	s_and_saveexec_b64 s[2:3], s[44:45]
	ds_write_b128 v34, v[30:33] offset:14336
	s_or_b64 exec, exec, s[2:3]
	s_and_b32 s68, s53, 7
	s_lshl_b32 s69, s68, 7
	v_or_b32_e32 v34, s69, v174
	v_lshlrev_b32_e32 v88, 2, v34
	v_lshl_add_u64 v[62:63], s[76:77], 0, v[88:89]
	v_add_co_u32_e32 v42, vcc, 0x3000, v62
	global_load_dwordx4 v[34:37], v88, s[76:77] offset:16
	global_load_dwordx4 v[38:41], v88, s[76:77]
	v_addc_co_u32_e32 v43, vcc, 0, v63, vcc
	global_load_dwordx4 v[50:53], v[42:43], off
	v_add_co_u32_e32 v42, vcc, 0x6000, v62
	s_mov_b64 s[2:3], 0x6000
	s_nop 0
	v_addc_co_u32_e32 v43, vcc, 0, v63, vcc
	v_add_co_u32_e32 v46, vcc, 0x9000, v62
	global_load_dwordx4 v[54:57], v[42:43], off
	s_nop 0
	v_addc_co_u32_e32 v47, vcc, 0, v63, vcc
	global_load_dwordx4 v[58:61], v[46:47], off
	v_lshl_add_u64 v[42:43], v[62:63], 0, s[2:3]
	s_mov_b64 s[2:3], 0x9000
	v_lshl_add_u64 v[46:47], v[62:63], 0, s[2:3]
	global_load_dwordx4 v[42:45], v[42:43], off offset:16
	s_mov_b64 s[2:3], 0x3000
	global_load_dwordx4 v[46:49], v[46:47], off offset:16
	v_lshl_add_u64 v[62:63], v[62:63], 0, s[2:3]
	global_load_dwordx4 v[62:65], v[62:63], off offset:16
	s_waitcnt vmcnt(8)
	v_lshlrev_b32_e32 v122, 16, v2
	v_and_b32_e32 v123, 0xffff0000, v2
	v_lshlrev_b32_e32 v66, 16, v6
	v_and_b32_e32 v68, 0xffff0000, v6
	v_mov_b32_e32 v67, v122
	v_mov_b32_e32 v69, v123
	v_lshlrev_b32_e32 v96, 16, v10
	v_and_b32_e32 v97, 0xffff0000, v10
	v_lshlrev_b32_e32 v104, 16, v14
	v_and_b32_e32 v105, 0xffff0000, v14
	v_mov_b32_e32 v124, v104
	v_mov_b32_e32 v125, v96
	v_mov_b32_e32 v126, v105
	v_mov_b32_e32 v127, v97
	v_lshlrev_b32_e32 v88, 16, v9
	v_lshlrev_b32_e32 v108, 16, v7
	v_and_b32_e32 v120, 0xffff0000, v7
	v_lshlrev_b32_e32 v109, 16, v3
	v_and_b32_e32 v121, 0xffff0000, v3
	v_lshlrev_b32_e32 v98, 16, v11
	v_and_b32_e32 v99, 0xffff0000, v11
	v_and_b32_e32 v107, 0xffff0000, v15
	v_lshlrev_b32_e32 v106, 16, v15
	v_lshlrev_b32_e32 v100, 16, v12
	v_lshlrev_b32_e32 v114, 16, v16
	v_mov_b32_e32 v128, v106
	v_mov_b32_e32 v129, v98
	v_mov_b32_e32 v130, v107
	v_mov_b32_e32 v131, v99
	v_and_b32_e32 v101, 0xffff0000, v12
	v_and_b32_e32 v115, 0xffff0000, v16
	v_lshlrev_b32_e32 v102, 16, v8
	v_and_b32_e32 v118, 0xffff0000, v8
	v_and_b32_e32 v110, 0xffff0000, v9
	v_and_b32_e32 v111, 0xffff0000, v5
	s_and_b32 s71, s41, 0xffffffc0
	s_waitcnt vmcnt(7)
	v_mul_f32_e32 v133, v36, v88
	s_waitcnt vmcnt(6)
	v_mov_b32_e32 v134, v38
	v_mov_b32_e32 v136, v39
	v_mov_b32_e32 v138, v40
	s_waitcnt vmcnt(5)
	v_mov_b32_e32 v135, v50
	v_mov_b32_e32 v137, v51
	v_pk_mul_f32 v[66:67], v[134:135], v[66:67]
	v_pk_mul_f32 v[68:69], v[136:137], v[68:69]
	v_mov_b32_e32 v248, v66
	v_mov_b32_e32 v249, v68
	v_pk_add_f32 v[248:249], v[248:249], 0 op_sel_hi:[1,0]
	v_mov_b32_e32 v68, v67
	s_waitcnt vmcnt(4)
	v_mov_b32_e32 v142, v54
	v_mov_b32_e32 v232, v55
	v_pk_add_f32 v[66:67], v[248:249], v[68:69]
	s_waitcnt vmcnt(3)
	v_mov_b32_e32 v143, v58
	v_mov_b32_e32 v233, v59
	v_pk_mul_f32 v[142:143], v[142:143], v[124:125]
	v_pk_mul_f32 v[232:233], v[232:233], v[126:127]
	v_mov_b32_e32 v68, v142
	v_mov_b32_e32 v69, v232
	v_pk_add_f32 v[66:67], v[66:67], v[68:69]
	v_mov_b32_e32 v232, v143
	v_pk_add_f32 v[66:67], v[66:67], v[232:233]
	v_mov_b32_e32 v140, v41
	v_mul_f32_e32 v68, 0xbfb8aa3b, v66
	v_exp_f32_e32 v68, v68
	v_mul_f32_e32 v69, 0xbfb8aa3b, v67
	v_exp_f32_e32 v88, v69
	v_mov_b32_e32 v139, v52
	v_add_f32_e32 v68, 1.0, v68
	v_rcp_f32_e32 v142, v68
	v_add_f32_e32 v68, 1.0, v88
	v_rcp_f32_e32 v143, v68
	v_mov_b32_e32 v141, v53
	v_pk_mul_f32 v[138:139], v[138:139], v[108:109]
	v_pk_mul_f32 v[140:141], v[140:141], v[120:121]
	v_mov_b32_e32 v134, v56
	v_mov_b32_e32 v136, v57
	v_mov_b32_e32 v135, v60
	v_mov_b32_e32 v137, v61
	v_pk_mul_f32 v[66:67], v[66:67], v[142:143]
	v_mov_b32_e32 v142, v140
	v_mov_b32_e32 v143, v138
	s_waitcnt vmcnt(2)
	v_mov_b32_e32 v238, v42
	v_pk_mul_f32 v[128:129], v[134:135], v[128:129]
	v_pk_mul_f32 v[130:131], v[136:137], v[130:131]
	s_waitcnt vmcnt(1)
	v_mov_b32_e32 v239, v46
	v_mov_b32_e32 v124, v114
	v_mov_b32_e32 v125, v100
	v_pk_add_f32 v[142:143], v[142:143], 0 op_sel_hi:[1,0]
	v_mov_b32_e32 v138, v141
	v_pk_mul_f32 v[134:135], v[238:239], v[124:125]
	v_mov_b32_e32 v124, v43
	v_mov_b32_e32 v125, v47
	v_mov_b32_e32 v126, v115
	v_mov_b32_e32 v127, v101
	v_pk_add_f32 v[138:139], v[142:143], v[138:139]
	v_mov_b32_e32 v140, v130
	v_mov_b32_e32 v141, v128
	v_pk_mul_f32 v[136:137], v[124:125], v[126:127]
	v_lshlrev_b32_e32 v124, 16, v4
	v_pk_add_f32 v[138:139], v[138:139], v[140:141]
	v_mov_b32_e32 v128, v131
	v_and_b32_e32 v125, 0xffff0000, v4
	v_mov_b32_e32 v126, v34
	s_waitcnt vmcnt(0)
	v_mov_b32_e32 v127, v62
	v_mov_b32_e32 v103, v124
	v_pk_add_f32 v[128:129], v[138:139], v[128:129]
	v_pk_mul_f32 v[238:239], v[126:127], v[102:103]
	v_mov_b32_e32 v102, v35
	v_mov_b32_e32 v103, v63
	v_mov_b32_e32 v119, v125
	v_mul_f32_e32 v68, 0xbfb8aa3b, v129
	v_pk_mul_f32 v[240:241], v[102:103], v[118:119]
	v_exp_f32_e32 v68, v68
	v_mul_f32_e32 v88, 0xbfb8aa3b, v128
	v_exp_f32_e32 v88, v88
	v_mov_b32_e32 v140, v240
	v_mov_b32_e32 v141, v238
	v_pk_add_f32 v[140:141], v[140:141], 0 op_sel_hi:[1,0]
	v_mov_b32_e32 v238, v241
	v_pk_add_f32 v[140:141], v[140:141], v[238:239]
	v_mov_b32_e32 v142, v136
	v_mov_b32_e32 v143, v134
	v_add_f32_e32 v68, 1.0, v68
	v_pk_add_f32 v[140:141], v[140:141], v[142:143]
	v_mov_b32_e32 v134, v137
	v_rcp_f32_e32 v139, v68
	v_add_f32_e32 v68, 1.0, v88
	v_pk_add_f32 v[134:135], v[140:141], v[134:135]
	v_rcp_f32_e32 v138, v68
	v_mul_f32_e32 v68, 0xbfb8aa3b, v135
	v_exp_f32_e32 v68, v68
	v_and_b32_e32 v103, 0xffff0000, v13
	v_and_b32_e32 v119, 0xffff0000, v17
	v_mov_b32_e32 v232, v37
	v_mov_b32_e32 v233, v65
	v_mov_b32_e32 v126, v45
	v_mov_b32_e32 v127, v49
	v_mov_b32_e32 v246, v119
	v_mov_b32_e32 v247, v103
	v_pk_mul_f32 v[232:233], v[232:233], v[110:111]
	v_pk_mul_f32 v[246:247], v[126:127], v[246:247]
	v_lshlrev_b32_e32 v126, 16, v5
	v_add_f32_e32 v68, 1.0, v68
	v_mov_b32_e32 v132, v232
	v_lshlrev_b32_e32 v118, 16, v17
	v_mul_f32_e32 v69, v64, v126
	v_rcp_f32_e32 v137, v68
	v_pk_add_f32 v[132:133], v[132:133], 0 op_sel_hi:[1,0]
	v_mov_b32_e32 v68, v233
	v_lshlrev_b32_e32 v102, 16, v13
	v_mul_f32_e32 v245, v44, v118
	v_pk_add_f32 v[68:69], v[132:133], v[68:69]
	v_mov_b32_e32 v244, v246
	v_mul_f32_e32 v243, v48, v102
	v_pk_add_f32 v[68:69], v[68:69], v[244:245]
	v_mov_b32_e32 v242, v247
	v_mul_f32_e32 v88, 0xbfb8aa3b, v134
	v_pk_add_f32 v[68:69], v[68:69], v[242:243]
	v_exp_f32_e32 v88, v88
	v_mul_f32_e32 v91, 0xbfb8aa3b, v69
	v_exp_f32_e32 v91, v91
	v_mul_f32_e32 v95, 0xbfb8aa3b, v68
	v_exp_f32_e32 v95, v95
	v_add_f32_e32 v88, 1.0, v88
	v_rcp_f32_e32 v136, v88
	v_add_f32_e32 v88, 1.0, v91
	v_rcp_f32_e32 v133, v88
	v_add_f32_e32 v88, 1.0, v95
	v_pk_mul_f32 v[130:131], v[66:67], v[66:67]
	v_pk_mul_f32 v[128:129], v[128:129], v[138:139]
	v_rcp_f32_e32 v132, v88
	v_pk_mul_f32 v[138:139], v[128:129], v[128:129]
	v_add_f32_e32 v88, v130, v131
	v_pk_mul_f32 v[134:135], v[134:135], v[136:137]
	v_add_f32_e32 v88, v139, v88
	v_pk_mul_f32 v[136:137], v[134:135], v[134:135]
	v_add_f32_e32 v88, v138, v88
	v_pk_mul_f32 v[68:69], v[68:69], v[132:133]
	v_add_f32_e32 v88, v137, v88
	v_pk_mul_f32 v[132:133], v[68:69], v[68:69]
	v_add_f32_e32 v88, v136, v88
	v_add_f32_e32 v88, v133, v88
	v_add_f32_e32 v88, v132, v88
	s_nop 1
	v_add_f32_dpp v88, v88, v88 quad_perm:[1,0,3,2] row_mask:0xf bank_mask:0xf
	s_nop 1
	v_add_f32_dpp v88, v88, v88 quad_perm:[2,3,0,1] row_mask:0xf bank_mask:0xf
	s_nop 1
	v_add_f32_dpp v88, v88, v88 row_ror:4 row_mask:0xf bank_mask:0xf
	s_nop 1
	v_add_f32_dpp v88, v88, v88 row_ror:8 row_mask:0xf bank_mask:0xf
	v_add_f32_e32 v88, 0x358637bd, v88
	v_mul_f32_e32 v91, 0x4b800000, v88
	v_cmp_gt_f32_e32 vcc, s52, v88
	s_nop 1
	v_cndmask_b32_e32 v88, v88, v91, vcc
	v_rsq_f32_e32 v88, v88
	s_nop 0
	v_mul_f32_e32 v91, 0x45800000, v88
	v_cndmask_b32_e32 v88, v88, v91, vcc
	v_mul_f32_e32 v88, v179, v88
	v_mul_f32_e32 v116, v66, v88
	v_mul_f32_e32 v232, v67, v88
	v_mul_f32_e32 v112, v129, v88
	v_mul_f32_e32 v231, v128, v88
	v_mul_f32_e32 v110, v135, v88
	v_mul_f32_e32 v95, v134, v88
	v_mul_f32_e32 v108, v69, v88
	v_mul_f32_e32 v91, v68, v88
	v_cvt_pk_bf16_f32 v66, v116, v232
	v_cvt_pk_bf16_f32 v67, v112, v231
	v_cvt_pk_bf16_f32 v68, v110, v95
	v_cvt_pk_bf16_f32 v69, v108, v91
	v_lshlrev_b32_e32 v88, 1, v86
	ds_write_b128 v224, v[66:69]
	s_and_saveexec_b64 s[2:3], s[38:39]
	s_cbranch_execz .LBB0_319
	v_add_u32_e32 v128, s71, v180
	v_ashrrev_i32_e32 v129, 31, v128
	v_lshlrev_b64 v[128:129], 11, v[128:129]
	v_lshl_add_u64 v[128:129], s[72:73], 0, v[128:129]
	s_lshl_b32 s80, s69, 1
	v_lshl_add_u64 v[128:129], v[128:129], 0, s[80:81]
	v_lshl_add_u64 v[128:129], v[128:129], 0, v[88:89]
	global_store_dwordx4 v[128:129], v[66:69], off
.LBB0_319:
	s_or_b64 exec, exec, s[2:3]
	s_nop 0
	v_pk_fma_f32 v[66:67], v[38:39], v[122:123], 0 op_sel_hi:[1,1,0]
	v_lshlrev_b32_e32 v128, 16, v22
	v_pk_fma_f32 v[66:67], v[50:51], v[104:105], v[66:67]
	v_and_b32_e32 v129, 0xffff0000, v22
	v_pk_fma_f32 v[66:67], v[54:55], v[96:97], v[66:67]
	v_mov_b32_e32 v120, v109
	v_pk_fma_f32 v[66:67], v[58:59], v[128:129], v[66:67]
	v_mov_b32_e32 v127, v111
	v_mul_f32_e32 v109, 0xbfb8aa3b, v66
	v_exp_f32_e32 v109, v109
	v_mul_f32_e32 v111, 0xbfb8aa3b, v67
	v_exp_f32_e32 v111, v111
	v_pk_fma_f32 v[68:69], v[40:41], v[120:121], 0 op_sel_hi:[1,1,0]
	v_pk_fma_f32 v[120:121], v[34:35], v[124:125], 0 op_sel_hi:[1,1,0]
	v_pk_fma_f32 v[68:69], v[52:53], v[106:107], v[68:69]
	v_lshlrev_b32_e32 v130, 16, v23
	v_and_b32_e32 v131, 0xffff0000, v23
	v_pk_fma_f32 v[68:69], v[56:57], v[98:99], v[68:69]
	v_pk_fma_f32 v[120:121], v[62:63], v[114:115], v[120:121]
	v_add_f32_e32 v109, 1.0, v109
	v_pk_fma_f32 v[68:69], v[60:61], v[130:131], v[68:69]
	v_lshlrev_b32_e32 v132, 16, v24
	v_and_b32_e32 v133, 0xffff0000, v24
	v_pk_fma_f32 v[120:121], v[42:43], v[100:101], v[120:121]
	v_rcp_f32_e32 v124, v109
	v_add_f32_e32 v109, 1.0, v111
	v_pk_fma_f32 v[120:121], v[46:47], v[132:133], v[120:121]
	v_rcp_f32_e32 v125, v109
	v_mul_f32_e32 v109, 0xbfb8aa3b, v68
	v_pk_fma_f32 v[122:123], v[36:37], v[126:127], 0 op_sel_hi:[1,1,0]
	v_exp_f32_e32 v109, v109
	v_mul_f32_e32 v111, 0xbfb8aa3b, v69
	v_mul_f32_e32 v126, 0xbfb8aa3b, v120
	v_exp_f32_e32 v111, v111
	v_exp_f32_e32 v127, v126
	v_pk_fma_f32 v[122:123], v[64:65], v[118:119], v[122:123]
	v_lshlrev_b32_e32 v134, 16, v25
	v_and_b32_e32 v135, 0xffff0000, v25
	v_pk_fma_f32 v[122:123], v[44:45], v[102:103], v[122:123]
	v_add_f32_e32 v109, 1.0, v109
	v_pk_fma_f32 v[122:123], v[48:49], v[134:135], v[122:123]
	v_rcp_f32_e32 v126, v109
	v_add_f32_e32 v109, 1.0, v111
	v_add_f32_e32 v111, 1.0, v127
	v_mul_f32_e32 v127, 0xbfb8aa3b, v122
	v_exp_f32_e32 v127, v127
	v_mul_f32_e32 v137, 0xbfb8aa3b, v123
	v_exp_f32_e32 v137, v137
	v_rcp_f32_e32 v136, v111
	v_mul_f32_e32 v111, 0xbfb8aa3b, v121
	v_exp_f32_e32 v111, v111
	v_add_f32_e32 v127, 1.0, v127
	v_rcp_f32_e32 v138, v127
	v_add_f32_e32 v127, 1.0, v137
	v_rcp_f32_e32 v139, v127
	v_rcp_f32_e32 v127, v109
	v_add_f32_e32 v111, 1.0, v111
	v_rcp_f32_e32 v137, v111
	v_pk_mul_f32 v[66:67], v[66:67], v[124:125]
	v_pk_mul_f32 v[68:69], v[68:69], v[126:127]
	v_pk_mul_f32 v[124:125], v[66:67], v[66:67]
	v_pk_mul_f32 v[126:127], v[68:69], v[68:69]
	v_add_f32_e32 v109, v124, v125
	v_pk_mul_f32 v[120:121], v[120:121], v[136:137]
	v_add_f32_e32 v109, v126, v109
	v_pk_mul_f32 v[136:137], v[120:121], v[120:121]
	v_add_f32_e32 v109, v127, v109
	v_pk_mul_f32 v[138:139], v[122:123], v[138:139]
	v_add_f32_e32 v109, v136, v109
	v_pk_mul_f32 v[122:123], v[138:139], v[138:139]
	v_add_f32_e32 v109, v137, v109
	v_add_f32_e32 v109, v122, v109
	v_add_f32_e32 v109, v123, v109
	s_nop 1
	v_add_f32_dpp v109, v109, v109 quad_perm:[1,0,3,2] row_mask:0xf bank_mask:0xf
	s_nop 1
	v_add_f32_dpp v109, v109, v109 quad_perm:[2,3,0,1] row_mask:0xf bank_mask:0xf
	s_nop 1
	v_add_f32_dpp v109, v109, v109 row_ror:4 row_mask:0xf bank_mask:0xf
	s_nop 1
	v_add_f32_dpp v109, v109, v109 row_ror:8 row_mask:0xf bank_mask:0xf
	v_add_f32_e32 v109, 0x358637bd, v109
	v_mul_f32_e32 v111, 0x4b800000, v109
	v_cmp_gt_f32_e32 vcc, s52, v109
	s_nop 1
	v_cndmask_b32_e32 v109, v109, v111, vcc
	v_rsq_f32_e32 v109, v109
	s_nop 0
	v_mul_f32_e32 v111, 0x45800000, v109
	v_cndmask_b32_e32 v109, v109, v111, vcc
	v_mul_f32_e32 v136, v179, v109
	v_pk_mul_f32 v[126:127], v[66:67], v[136:137] op_sel_hi:[1,0]
	v_pk_mul_f32 v[124:125], v[68:69], v[136:137] op_sel_hi:[1,0]
	v_pk_mul_f32 v[122:123], v[120:121], v[136:137] op_sel_hi:[1,0]
	v_pk_mul_f32 v[120:121], v[138:139], v[136:137] op_sel_hi:[1,0]
	v_cvt_pk_bf16_f32 v66, v126, v127
	v_cvt_pk_bf16_f32 v67, v124, v125
	v_cvt_pk_bf16_f32 v68, v122, v123
	v_cvt_pk_bf16_f32 v69, v120, v121
	ds_write_b128 v224, v[66:69] offset:272
	s_and_saveexec_b64 s[2:3], s[38:39]
	s_cbranch_execz .LBB0_321
	v_add_u32_e32 v136, s71, v181
	v_ashrrev_i32_e32 v137, 31, v136
	v_lshlrev_b64 v[136:137], 11, v[136:137]
	v_lshl_add_u64 v[136:137], s[72:73], 0, v[136:137]
	s_lshl_b32 s80, s69, 1
	v_lshl_add_u64 v[136:137], v[136:137], 0, s[80:81]
	v_lshl_add_u64 v[136:137], v[136:137], 0, v[88:89]
	global_store_dwordx4 v[136:137], v[66:69], off
.LBB0_321:
	s_or_b64 exec, exec, s[2:3]
	s_nop 0
	v_pk_fma_f32 v[66:67], v[38:39], v[104:105], 0 op_sel_hi:[1,1,0]
	v_lshlrev_b32_e32 v142, 16, v18
	v_pk_fma_f32 v[66:67], v[50:51], v[96:97], v[66:67]
	v_and_b32_e32 v143, 0xffff0000, v18
	v_pk_fma_f32 v[66:67], v[54:55], v[128:129], v[66:67]
	v_pk_fma_f32 v[68:69], v[40:41], v[106:107], 0 op_sel_hi:[1,1,0]
	v_pk_fma_f32 v[66:67], v[58:59], v[142:143], v[66:67]
	v_pk_fma_f32 v[68:69], v[52:53], v[98:99], v[68:69]
	v_mul_f32_e32 v106, 0xbfb8aa3b, v66
	v_exp_f32_e32 v109, v106
	v_mul_f32_e32 v106, 0xbfb8aa3b, v67
	v_exp_f32_e32 v111, v106
	v_lshlrev_b32_e32 v140, 16, v19
	v_and_b32_e32 v141, 0xffff0000, v19
	v_pk_fma_f32 v[68:69], v[56:57], v[130:131], v[68:69]
	v_add_f32_e32 v109, 1.0, v109
	v_pk_fma_f32 v[68:69], v[60:61], v[140:141], v[68:69]
	v_pk_fma_f32 v[104:105], v[34:35], v[114:115], 0 op_sel_hi:[1,1,0]
	v_rcp_f32_e32 v114, v109
	v_add_f32_e32 v109, 1.0, v111
	v_rcp_f32_e32 v115, v109
	v_mul_f32_e32 v109, 0xbfb8aa3b, v68
	v_exp_f32_e32 v109, v109
	v_mul_f32_e32 v111, 0xbfb8aa3b, v69
	v_exp_f32_e32 v111, v111
	v_pk_fma_f32 v[104:105], v[62:63], v[100:101], v[104:105]
	v_lshlrev_b32_e32 v138, 16, v20
	v_and_b32_e32 v139, 0xffff0000, v20
	v_pk_fma_f32 v[104:105], v[42:43], v[132:133], v[104:105]
	v_add_f32_e32 v109, 1.0, v109
	v_pk_fma_f32 v[104:105], v[46:47], v[138:139], v[104:105]
	v_pk_fma_f32 v[106:107], v[36:37], v[118:119], 0 op_sel_hi:[1,1,0]
	v_rcp_f32_e32 v118, v109
	v_add_f32_e32 v109, 1.0, v111
	v_rcp_f32_e32 v119, v109
	v_mul_f32_e32 v109, 0xbfb8aa3b, v104
	v_exp_f32_e32 v109, v109
	v_mul_f32_e32 v111, 0xbfb8aa3b, v105
	v_exp_f32_e32 v111, v111
	v_pk_fma_f32 v[106:107], v[64:65], v[102:103], v[106:107]
	v_lshlrev_b32_e32 v136, 16, v21
	v_and_b32_e32 v137, 0xffff0000, v21
	v_pk_fma_f32 v[106:107], v[44:45], v[134:135], v[106:107]
	v_add_f32_e32 v109, 1.0, v109
	v_pk_fma_f32 v[106:107], v[48:49], v[136:137], v[106:107]
	v_pk_mul_f32 v[68:69], v[68:69], v[118:119]
	v_rcp_f32_e32 v118, v109
	v_add_f32_e32 v109, 1.0, v111
	v_mul_f32_e32 v111, 0xbfb8aa3b, v106
	v_exp_f32_e32 v111, v111
	v_mul_f32_e32 v119, 0xbfb8aa3b, v107
	v_exp_f32_e32 v233, v119
	v_rcp_f32_e32 v119, v109
	v_add_f32_e32 v109, 1.0, v111
	v_pk_mul_f32 v[66:67], v[66:67], v[114:115]
	v_rcp_f32_e32 v238, v109
	v_add_f32_e32 v109, 1.0, v233
	v_pk_mul_f32 v[114:115], v[66:67], v[66:67]
	v_rcp_f32_e32 v239, v109
	v_pk_mul_f32 v[240:241], v[68:69], v[68:69]
	v_add_f32_e32 v109, v114, v115
	v_pk_mul_f32 v[104:105], v[104:105], v[118:119]
	v_add_f32_e32 v109, v240, v109
	v_pk_mul_f32 v[118:119], v[104:105], v[104:105]
	v_add_f32_e32 v109, v241, v109
	v_pk_mul_f32 v[238:239], v[106:107], v[238:239]
	v_add_f32_e32 v109, v118, v109
	v_pk_mul_f32 v[106:107], v[238:239], v[238:239]
	v_add_f32_e32 v109, v119, v109
	v_add_f32_e32 v106, v106, v109
	v_add_f32_e32 v106, v107, v106
	s_nop 1
	v_add_f32_dpp v106, v106, v106 quad_perm:[1,0,3,2] row_mask:0xf bank_mask:0xf
	s_nop 1
	v_add_f32_dpp v106, v106, v106 quad_perm:[2,3,0,1] row_mask:0xf bank_mask:0xf
	s_nop 1
	v_add_f32_dpp v106, v106, v106 row_ror:4 row_mask:0xf bank_mask:0xf
	s_nop 1
	v_add_f32_dpp v106, v106, v106 row_ror:8 row_mask:0xf bank_mask:0xf
	v_add_f32_e32 v106, 0x358637bd, v106
	v_mul_f32_e32 v107, 0x4b800000, v106
	v_cmp_gt_f32_e32 vcc, s52, v106
	s_nop 1
	v_cndmask_b32_e32 v106, v106, v107, vcc
	v_rsq_f32_e32 v106, v106
	s_nop 0
	v_mul_f32_e32 v107, 0x45800000, v106
	v_cndmask_b32_e32 v106, v106, v107, vcc
	v_mul_f32_e32 v115, v179, v106
	v_mul_f32_e32 v118, v66, v115
	v_mul_f32_e32 v111, v67, v115
	v_mul_f32_e32 v114, v68, v115
	v_mul_f32_e32 v109, v69, v115
	v_mul_f32_e32 v106, v104, v115
	v_mul_f32_e32 v107, v105, v115
	v_mul_f32_e32 v104, v238, v115
	v_mul_f32_e32 v105, v239, v115
	v_cvt_pk_bf16_f32 v66, v118, v111
	v_cvt_pk_bf16_f32 v67, v114, v109
	v_cvt_pk_bf16_f32 v68, v106, v107
	v_cvt_pk_bf16_f32 v69, v104, v105
	ds_write_b128 v224, v[66:69] offset:544
	s_and_saveexec_b64 s[2:3], s[38:39]
	s_cbranch_execz .LBB0_323
	v_add_u32_e32 v238, s71, v182
	v_ashrrev_i32_e32 v239, 31, v238
	v_lshlrev_b64 v[238:239], 11, v[238:239]
	v_lshl_add_u64 v[238:239], s[72:73], 0, v[238:239]
	s_lshl_b32 s80, s69, 1
	v_lshl_add_u64 v[238:239], v[238:239], 0, s[80:81]
	v_lshl_add_u64 v[238:239], v[238:239], 0, v[88:89]
	global_store_dwordx4 v[238:239], v[66:69], off
.LBB0_323:
	s_or_b64 exec, exec, s[2:3]
	v_pk_fma_f32 v[38:39], v[38:39], v[96:97], 0 op_sel_hi:[1,1,0]
	v_pk_fma_f32 v[36:37], v[36:37], v[102:103], 0 op_sel_hi:[1,1,0]
	v_pk_fma_f32 v[38:39], v[50:51], v[128:129], v[38:39]
	v_lshlrev_b32_e32 v50, 16, v26
	v_pk_fma_f32 v[38:39], v[54:55], v[142:143], v[38:39]
	v_and_b32_e32 v51, 0xffff0000, v26
	v_pk_fma_f32 v[38:39], v[58:59], v[50:51], v[38:39]
	v_pk_fma_f32 v[36:37], v[64:65], v[134:135], v[36:37]
	v_pk_fma_f32 v[40:41], v[40:41], v[98:99], 0 op_sel_hi:[1,1,0]
	v_pk_fma_f32 v[36:37], v[44:45], v[136:137], v[36:37]
	v_mul_f32_e32 v44, 0xbfb8aa3b, v38
	v_mul_f32_e32 v45, 0xbfb8aa3b, v39
	v_pk_fma_f32 v[34:35], v[34:35], v[100:101], 0 op_sel_hi:[1,1,0]
	v_exp_f32_e32 v44, v44
	v_exp_f32_e32 v45, v45
	v_pk_fma_f32 v[40:41], v[52:53], v[130:131], v[40:41]
	v_pk_fma_f32 v[34:35], v[62:63], v[132:133], v[34:35]
	v_pk_fma_f32 v[40:41], v[56:57], v[140:141], v[40:41]
	v_lshlrev_b32_e32 v50, 16, v27
	v_and_b32_e32 v51, 0xffff0000, v27
	v_pk_fma_f32 v[34:35], v[42:43], v[138:139], v[34:35]
	v_lshlrev_b32_e32 v42, 16, v28
	v_and_b32_e32 v43, 0xffff0000, v28
	v_pk_fma_f32 v[40:41], v[60:61], v[50:51], v[40:41]
	v_pk_fma_f32 v[34:35], v[46:47], v[42:43], v[34:35]
	v_lshlrev_b32_e32 v42, 16, v29
	v_and_b32_e32 v43, 0xffff0000, v29
	v_pk_fma_f32 v[36:37], v[48:49], v[42:43], v[36:37]
	v_add_f32_e32 v42, 1.0, v44
	v_add_f32_e32 v43, 1.0, v45
	v_mul_f32_e32 v44, 0xbfb8aa3b, v40
	v_mul_f32_e32 v45, 0xbfb8aa3b, v41
	v_exp_f32_e32 v44, v44
	v_exp_f32_e32 v45, v45
	v_mul_f32_e32 v46, 0xbfb8aa3b, v34
	v_mul_f32_e32 v47, 0xbfb8aa3b, v35
	v_exp_f32_e32 v46, v46
	v_exp_f32_e32 v47, v47
	v_mul_f32_e32 v48, 0xbfb8aa3b, v36
	v_mul_f32_e32 v49, 0xbfb8aa3b, v37
	v_rcp_f32_e32 v42, v42
	v_rcp_f32_e32 v43, v43
	v_add_f32_e32 v44, 1.0, v44
	v_add_f32_e32 v45, 1.0, v45
	v_exp_f32_e32 v48, v48
	v_exp_f32_e32 v49, v49
	v_rcp_f32_e32 v44, v44
	v_rcp_f32_e32 v45, v45
	v_add_f32_e32 v46, 1.0, v46
	v_add_f32_e32 v47, 1.0, v47
	v_rcp_f32_e32 v46, v46
	v_rcp_f32_e32 v47, v47
	v_add_f32_e32 v48, 1.0, v48
	v_add_f32_e32 v49, 1.0, v49
	v_pk_mul_f32 v[38:39], v[38:39], v[42:43]
	v_rcp_f32_e32 v48, v48
	v_rcp_f32_e32 v49, v49
	v_pk_mul_f32 v[40:41], v[40:41], v[44:45]
	v_pk_mul_f32 v[42:43], v[38:39], v[38:39]
	v_pk_mul_f32 v[44:45], v[40:41], v[40:41]
	v_add_f32_e32 v42, v42, v43
	v_pk_mul_f32 v[34:35], v[34:35], v[46:47]
	v_add_f32_e32 v42, v44, v42
	v_pk_mul_f32 v[46:47], v[34:35], v[34:35]
	v_add_f32_e32 v42, v45, v42
	v_pk_mul_f32 v[36:37], v[36:37], v[48:49]
	v_add_f32_e32 v42, v46, v42
	v_pk_mul_f32 v[48:49], v[36:37], v[36:37]
	v_add_f32_e32 v42, v47, v42
	v_add_f32_e32 v42, v48, v42
	v_add_f32_e32 v42, v49, v42
	s_nop 1
	v_add_f32_dpp v42, v42, v42 quad_perm:[1,0,3,2] row_mask:0xf bank_mask:0xf
	s_nop 1
	v_add_f32_dpp v42, v42, v42 quad_perm:[2,3,0,1] row_mask:0xf bank_mask:0xf
	s_nop 1
	v_add_f32_dpp v42, v42, v42 row_ror:4 row_mask:0xf bank_mask:0xf
	s_nop 1
	v_add_f32_dpp v42, v42, v42 row_ror:8 row_mask:0xf bank_mask:0xf
	v_add_f32_e32 v42, 0x358637bd, v42
	v_mul_f32_e32 v43, 0x4b800000, v42
	v_cmp_gt_f32_e32 vcc, s52, v42
	s_nop 1
	v_cndmask_b32_e32 v42, v42, v43, vcc
	v_rsq_f32_e32 v42, v42
	s_nop 0
	v_mul_f32_e32 v43, 0x45800000, v42
	v_cndmask_b32_e32 v42, v42, v43, vcc
	v_mul_f32_e32 v46, v179, v42
	v_pk_mul_f32 v[44:45], v[38:39], v[46:47] op_sel_hi:[1,0]
	v_pk_mul_f32 v[42:43], v[40:41], v[46:47] op_sel_hi:[1,0]
	v_pk_mul_f32 v[40:41], v[34:35], v[46:47] op_sel_hi:[1,0]
	v_pk_mul_f32 v[38:39], v[36:37], v[46:47] op_sel_hi:[1,0]
	v_cvt_pk_bf16_f32 v34, v44, v45
	v_cvt_pk_bf16_f32 v35, v42, v43
	v_cvt_pk_bf16_f32 v36, v40, v41
	v_cvt_pk_bf16_f32 v37, v38, v39
	ds_write_b128 v211, v[34:37]
	s_and_saveexec_b64 s[2:3], s[46:47]
	s_xor_b64 s[2:3], exec, s[2:3]
	s_cbranch_execz .LBB0_325
	v_cvt_pk_bf16_f32 v34, v116, v126
	v_cvt_pk_bf16_f32 v35, v118, v44
	global_store_dwordx2 v[84:85], v[34:35], off offset:-512
	v_cvt_pk_bf16_f32 v34, v232, v127
	v_cvt_pk_bf16_f32 v35, v111, v45
	global_store_dwordx2 v[84:85], v[34:35], off offset:-384
	v_cvt_pk_bf16_f32 v34, v112, v124
	v_cvt_pk_bf16_f32 v35, v114, v42
	global_store_dwordx2 v[84:85], v[34:35], off offset:-256
	v_cvt_pk_bf16_f32 v34, v231, v125
	v_cvt_pk_bf16_f32 v35, v109, v43
	global_store_dwordx2 v[84:85], v[34:35], off offset:-128
	v_cvt_pk_bf16_f32 v34, v110, v122
	v_cvt_pk_bf16_f32 v35, v106, v40
	global_store_dwordx2 v[84:85], v[34:35], off
	v_cvt_pk_bf16_f32 v34, v95, v123
	v_cvt_pk_bf16_f32 v35, v107, v41
	global_store_dwordx2 v[84:85], v[34:35], off offset:128
	v_cvt_pk_bf16_f32 v34, v108, v120
	v_cvt_pk_bf16_f32 v35, v104, v38
	global_store_dwordx2 v[84:85], v[34:35], off offset:256
	v_cvt_pk_bf16_f32 v34, v91, v121
	v_cvt_pk_bf16_f32 v35, v105, v39
	global_store_dwordx2 v[84:85], v[34:35], off offset:384
